# static s_setprio 1 for waves 4-7 during the sparse-attention phase (reset to 0 at its end); on top of v35
# baseline (speedup 1.0000x reference)
; #define LAS __attribute__((address_space(3)))
; __device__ __forceinline__ unsigned xb_ld(unsigned* p)              { return __hip_atomic_load(p, __ATOMIC_RELAXED, __HIP_MEMORY_SCOPE_AGENT); }
; __device__ __forceinline__ void nsa_unit(int unit, const bf16_t* proj, const bf16_t* kc, const bf16_t* vc, const bf16_t* gn, const float* cs, const float* sn, ...
;     const int l16 = lane & 15, kq = lane >> 4;
;     const int g = unit & 1, tb = unit >> 1, t0 = 4 * tb, qi = l16 >> 2, h = l16 & 3, tc = t0 + qi, head = 4 * g + h;
;     LAS unsigned char* vbuf = wl; LAS float* imp = (LAS float*)(wl + VBUF_BYTES); LAS int* sel = (LAS int*)(wl + VBUF_BYTES + 4 * IMP_LD * 4);
;     bf16x8 qf[4];
;     { const bf16_t* qrow = proj + (size_t)tc * PLD + PC_QA + head * 128 + 8 * kq;
; #pragma unroll
;         for (int s = 0; s < 4; ++s) qf[s] = *(const bf16x8*)(qrow + 32 * s); }
;     LAS u32x2* outl = (LAS u32x2*)(wl + OUT_OFF) + lane;
;     for (int i = lane; i < 4 * IMP_LD; i += 64) imp[i] = 0.f;
;     const int hic = (tc - 31) >> 4;
;     const int nkmax = ((t0 + 3 - 31) >> 4) + 1, nsc = nkmax > 0 ? (nkmax + 31) >> 5 : 0;
;     unsigned long long coff = (unsigned long long)g * 1024 * 128; asm volatile("" : "+s"(coff));
;     const bf16_t* kcg = kc + coff; const bf16_t* vcg = vc + coff;
;     AState st; astate_init(st);
; __global__ void __launch_bounds__(512, 2) fwd_megakernel(Params P) {
;     ...
;     { PHASE_WS;
;       int vb = (int)blockIdx.x;
;       { bool ok = true; unsigned* cen = (unsigned*)P.ws;
; #pragma unroll
;         for (int j = 0; j < 8; ++j) ok &= (xb_ld(&cen[XB_XCNT(j)]) * 8u == (unsigned)G);
;         if (ok) vb = vbid; }
;       if ((G & 7) == 0) {
;           const int bx = vb, x = bx & 7, g = x & 1, wj = ((bx >> 3) * 4 + (x >> 1)) * 8 + wave, nwj = (G >> 1) * 8;
;           for (int k = 0; k * nwj < 4096; ++k) {
;               const int tb = k * nwj + ((k & 1) ? (nwj - 1 - wj) : wj);
;               if (tb < 4096) nsa_unit(2 * tb + g, PROJ, KC, VC, GN, RCOS, RSIN, KSLF, VSLF, KWNF, VWNF, NSAOUT, wl, lane); }
.LBB0_822:
	s_or_b64 exec, exec, s[4:5]
	s_mov_b64 s[48:49], s[36:37]
	s_waitcnt lgkmcnt(0)
	v_mov_b32_e32 v0, 0
	v_mov_b32_e32 v1, 0
	s_barrier
	global_load_dword v2, v0, s[36:37] offset:1024 sc1
	global_load_dword v3, v0, s[36:37] offset:1280 sc1
	global_load_dword v4, v0, s[36:37] offset:1536 sc1
	global_load_dword v5, v0, s[36:37] offset:1792 sc1
	global_load_dword v6, v0, s[36:37] offset:2048 sc1
	global_load_dword v7, v0, s[36:37] offset:2304 sc1
	global_load_dword v8, v0, s[36:37] offset:2560 sc1
	global_load_dword v9, v0, s[36:37] offset:2816 sc1
	v_mbcnt_lo_u32_b32 v0, -1, v1
	v_mbcnt_hi_u32_b32 v207, -1, v0
	v_add_u32_e32 v0, s33, v207
	s_andn2_b64 vcc, exec, s[20:21]
	v_readfirstlane_b32 s10, v0
	s_ashr_i32 s60, s10, 6
	s_mul_i32 s3, s60, 0x4740
	s_cmp_lt_u32 s60, 4
	s_cbranch_scc1 .Lnsa_prio_done
	s_setprio 1
.Lnsa_prio_done:
	v_and_b32_e32 v206, 63, v207
	s_add_i32 s3, s3, 0
	s_waitcnt vmcnt(7)
	v_readfirstlane_b32 s71, v2
	s_waitcnt vmcnt(6)
	v_readfirstlane_b32 s70, v3
	s_waitcnt vmcnt(5)
	v_readfirstlane_b32 s69, v4
	s_waitcnt vmcnt(4)
	v_readfirstlane_b32 s68, v5
	s_waitcnt vmcnt(3)
	v_readfirstlane_b32 s67, v6
	s_waitcnt vmcnt(2)
	v_readfirstlane_b32 s63, v7
	s_waitcnt vmcnt(1)
	v_readfirstlane_b32 s62, v8
	s_waitcnt vmcnt(0)
	v_readfirstlane_b32 s61, v9
	s_cbranch_vccnz .LBB0_923
	s_add_i32 s72, s60, s64
	s_mov_b32 s46, s93
	s_cmpk_gt_i32 s72, 0x1fff
	s_cbranch_scc1 .LBB0_922
	s_add_u32 s73, s48, 0x1a00000
	s_addc_u32 s74, s49, 0
	s_add_u32 s75, s48, 0x1a80000
	s_addc_u32 s76, s49, 0
	s_add_u32 s77, s48, 0x1a000000
	s_addc_u32 s78, s49, 0
	s_add_u32 s79, s48, 0x1a800000
	s_addc_u32 s80, s49, 0
	s_add_u32 s81, s48, 0x1b800000
	s_addc_u32 s82, s49, 0
	v_lshrrev_b32_e32 v208, 4, v206
	v_lshrrev_b32_e32 v2, 2, v206
	v_bfe_u32 v209, v206, 2, 2
	s_add_u32 s83, s48, 0x1b000000
	v_and_b32_e32 v4, 3, v207
	v_and_b32_e32 v211, 12, v2
	v_lshlrev_b32_e32 v212, 2, v208
	v_mul_u32_u24_e32 v2, 0x410, v209
	s_addc_u32 s84, s49, 0
	s_bfe_u32 s12, s10, 0x10006
	v_mov_b32_e32 v1, 0
	v_add3_u32 v213, s3, v2, v212
	v_lshlrev_b64 v[2:3], v206, -1
	v_lshl_or_b32 v7, s12, 2, v4
	v_not_b32_e32 v121, v3
	v_not_b32_e32 v120, v2
	v_lshlrev_b32_e32 v2, 8, v7
	v_mov_b32_e32 v3, v1
	v_cmp_eq_u32_e64 s[4:5], 0, v4
	v_and_b32_e32 v4, 48, v206
	v_mov_b32_e32 v5, v1
	v_lshl_add_u64 v[2:3], s[48:49], 0, v[2:3]
	v_lshl_add_u64 v[4:5], v[2:3], 0, v[4:5]
	s_mov_b64 s[10:11], 0xe000000
	v_lshl_add_u64 v[122:123], v[4:5], 0, s[10:11]
	v_mul_u32_u24_e32 v4, 3, v7
	v_lshlrev_b32_e32 v4, 1, v4
	v_mov_b32_e32 v5, v1
	v_lshlrev_b32_e32 v0, 3, v208
	v_lshl_add_u64 v[4:5], s[48:49], 0, v[4:5]
	s_mov_b64 s[10:11], 0x1b00000
	v_lshlrev_b32_e32 v118, 3, v206
	v_lshlrev_b32_e32 v214, 2, v206
	v_lshl_add_u64 v[124:125], v[4:5], 0, s[10:11]
	v_lshl_add_u64 v[2:3], v[2:3], 0, v[0:1]
	s_mov_b64 s[10:11], 0x1d200000
	v_lshlrev_b32_e32 v0, 5, v208
	v_add_u32_e32 v210, s3, v118
	v_lshl_add_u64 v[126:127], v[2:3], 0, s[10:11]
	v_lshl_add_u64 v[2:3], s[48:49], 0, v[0:1]
	s_mov_b64 s[10:11], 0x1c000000
	v_add_u32_e32 v0, s3, v214
	s_mov_b32 s51, 0
	v_add_u32_e32 v215, v210, v118
	v_mul_i32_i24_e32 v6, -12, v206
	s_lshl_b32 s50, s12, 17
	v_lshl_add_u64 v[128:129], v[2:3], 0, s[10:11]
	s_mov_b64 s[10:11], 0x1c400000
	v_add_u32_e32 v219, 0x2400, v0
	v_mbcnt_lo_u32_b32 v0, -1, 0
	v_mov_b32_e32 v119, v1
	v_cmp_eq_u32_e64 s[6:7], 0, v206
	v_or_b32_e32 v216, 1, v214
	v_or_b32_e32 v217, 2, v214
	v_or_b32_e32 v218, 3, v214
	v_cmp_gt_u32_e64 s[8:9], 16, v206
	s_lshl_b32 s52, s12, 21
	s_mov_b32 s53, s51
	v_lshl_add_u64 v[130:131], v[2:3], 0, s[10:11]
	v_or_b32_e32 v220, 0xffffffc0, v206
	s_add_i32 s85, s3, 0x3440
	s_mov_b64 s[54:55], s[50:51]
	s_movk_i32 s86, 0x1000
	s_mov_b32 s87, 0x3e0293ee
	s_movk_i32 s88, 0xffef
	s_movk_i32 s89, 0xffee
	s_movk_i32 s90, 0xffed
	s_movk_i32 s91, 0xffec
	v_mbcnt_hi_u32_b32 v221, -1, v0
	s_movk_i32 s92, 0xff
	s_movk_i32 s93, 0xfe
	s_movk_i32 s94, 0xfd
	s_movk_i32 s95, 0xfc
	v_add_u32_e32 v222, v215, v6
	v_mov_b32_e32 v223, 0xf149f2ca
	v_mov_b32_e32 v224, 0xffffff00
	v_mov_b32_e32 v225, 0x400
	s_branch .LBB0_827

; __device__ __forceinline__ unsigned xb_ld(unsigned* p)              { return __hip_atomic_load(p, __ATOMIC_RELAXED, __HIP_MEMORY_SCOPE_AGENT); }
; __device__ __forceinline__ unsigned xb_add(unsigned* p, unsigned v) { return __hip_atomic_fetch_add(p, v, __ATOMIC_RELAXED, __HIP_MEMORY_SCOPE_AGENT); }
; __device__ __forceinline__ void xcd_barrier_complete(unsigned* bar, unsigned x, unsigned& nloc, unsigned& nx) {
;     const unsigned G = gridDim.x * gridDim.y * gridDim.z;
;     unsigned sum, cnt, mine, sp = 0u;
;     for (;;) {
;         sum = 0u; cnt = 0u; mine = 0u;
; #pragma unroll
;         for (unsigned j = 0; j < 16; ++j) { const unsigned c = xb_ld(&bar[XB_XCNT(j)]); sum += c; cnt += (c > 0u) ? 1u : 0u; mine = (j == x) ? c : mine; }
; __device__ __forceinline__ void xcd_barrier(const XcdBarrier& b, const int tid) {
;     asm volatile("s_waitcnt vmcnt(0)" ::: "memory");
;     __syncthreads();
;     if (tid == 0) {
;         unsigned* bar = b.bar;
;         __builtin_amdgcn_s_waitcnt(0);
;         unsigned nloc = b.st[0], nx = b.st[1];
;         if (nloc == 0u) { xcd_barrier_complete(bar, b.x, nloc, nx); b.st[0] = nloc; b.st[1] = nx; }
;         const unsigned old = xb_add(&bar[XB_XSUB(b.x)], 1u);
.LBB0_1024:
	s_setprio 0
	v_mov_b32_e32 v0, 0
	s_waitcnt vmcnt(0) lgkmcnt(0)
	s_waitcnt vmcnt(0)
	s_waitcnt lgkmcnt(0)
	v_mbcnt_lo_u32_b32 v0, -1, v0
	v_mbcnt_hi_u32_b32 v0, -1, v0
	v_sub_u32_e32 v0, 0, v0
	v_cmp_eq_u32_e32 vcc, s33, v0
	s_barrier
	s_and_saveexec_b64 s[4:5], vcc
	s_cbranch_execz .LBB0_1076
	s_add_i32 s3, 0, 0x23a00
	v_mov_b32_e32 v0, s3
	s_waitcnt vmcnt(0) expcnt(0) lgkmcnt(0)
	ds_read_b32 v2, v0
	s_add_i32 s3, 0, 0x23a04
	v_mov_b32_e32 v0, s3
	ds_read_b32 v0, v0
	s_waitcnt lgkmcnt(1)
	v_cmp_ne_u32_e32 vcc, 0, v2
	s_cbranch_vccnz .LBB0_1040
	s_add_u32 s6, s36, 0x1000
	s_addc_u32 s7, s37, 0
	s_add_u32 s8, s36, 0x1100
	s_addc_u32 s9, s37, 0
	s_add_u32 s10, s36, 0x1200
	s_addc_u32 s11, s37, 0
	s_mul_i32 s3, s39, s93
	s_add_u32 s12, s36, 0x1300
	s_mul_i32 s3, s3, s38
	s_addc_u32 s13, s37, 0
	s_mov_b32 s20, 1
	v_mov_b32_e32 v16, 0
	s_branch .LBB0_1028
